# P2 p_win3 copy loop: 4 iterations of loads batched before one wait
# speedup vs baseline: 1.0056x; 1.0056x over previous
; DI float bflo(unsigned d) { return __uint_as_float(d << 16); }
; DI float bfhi(unsigned d) { return __uint_as_float(d & 0xffff0000u); }
; DI void phase2(const Params& p, char* smem) {
;     ...
;   for (int g = 0; g < 3; ++g) {
;     const int W = 128 << (2 * g);
;     const size_t off = (g == 0) ? O_PW1 : (g == 1 ? O_PW2 : O_PW3);
;     const size_t n4 = (size_t)4 * W * 512 / 4;
;     for (size_t i = gtid; i < n4; i += gsz) {
;       const size_t e0 = i * 4;
;       const int e = (int)(e0 & 511), ii = (int)((e0 >> 9) % W), b = (int)((e0 >> 9) / W);
;       uint2 v = *(const uint2*)&p.proj[((size_t)b * SEQ + SEQ - W + ii) * NP + 2048 + g * 768 + 256 + e];
;       *(float4*)&p.out[off + e0] = make_float4(bflo(v.x), bfhi(v.x), bflo(v.y), bfhi(v.y));
;     }
;   }
.LBB0_471:
	s_or_b64 exec, exec, s[0:1]
	s_mov_b64 s[0:1], 0x100000
	v_cmp_gt_u64_e32 vcc, s[0:1], v[10:11]
	s_and_saveexec_b64 s[0:1], vcc
	s_cbranch_execz .LBB0_474
	v_mov_b32_e32 v0, 0x10160
	v_mov_b32_e32 v1, 0x100d8
	s_waitcnt lgkmcnt(0)
	ds_read_b64 v[4:5], v1
	ds_read_b64 v[0:1], v0
	s_lshl_b64 s[2:3], s[86:87], 12
	v_mov_b32_e32 v3, 0
	v_mov_b32_e32 v141, v3
	s_waitcnt lgkmcnt(0)
	v_lshl_add_u64 v[4:5], v[4:5], 0, s[2:3]
	v_lshl_add_u64 v[4:5], v[4:5], 0, v[140:141]
	s_mov_b64 s[2:3], 0x8692000
	s_lshl_b64 s[6:7], s[86:87], 10
	v_mov_b32_e32 v147, v3
	v_lshl_add_u64 v[4:5], v[4:5], 0, s[2:3]
	s_lshl_b64 s[2:3], s[52:53], 12
	v_lshl_add_u64 v[6:7], s[6:7], 0, v[146:147]
	s_lshl_b64 s[6:7], s[52:53], 10
	s_mov_b64 s[10:11], 0
	s_movk_i32 s14, 0xe000
	s_movk_i32 s15, 0x2200
	s_mov_b32 s16, 0x3301000
	s_mov_b64 s[12:13], 0xfffff
	v_mov_b64_e32 v[8:9], v[10:11]
	s_lshl_b32 s93, s50, 2
	s_mov_b32 s92, s93
	s_cmp_le_u32 s92, 0x100000
	s_cbranch_scc0 .Lpw3_rest
.Lpw3_batch:
	v_lshrrev_b64 v[12:13], 5, v[8:9]
	v_bfe_u32 v14, v8, 7, 11
	v_and_or_b32 v12, v12, s14, v14
	v_mad_u64_u32 v[14:15], s[18:19], v12, s15, v[0:1]
	v_mov_b32_e32 v12, v15
	v_and_b32_e32 v2, 0x1fc, v6
	v_mad_u64_u32 v[12:13], s[18:19], v13, s15, v[12:13]
	v_lshlrev_b32_e32 v2, 1, v2
	v_mov_b32_e32 v15, v12
	v_lshl_add_u64 v[12:13], v[14:15], 0, v[2:3]
	v_add_co_u32_e32 v12, vcc, s16, v12
	v_lshl_add_u64 v[8:9], v[8:9], 0, s[50:51]
	s_nop 0
	v_addc_co_u32_e32 v13, vcc, 0, v13, vcc
	flat_load_dwordx2 v[220:221], v[12:13] offset:3584
	v_lshl_add_u64 v[6:7], v[6:7], 0, s[6:7]
	v_lshrrev_b64 v[12:13], 5, v[8:9]
	v_bfe_u32 v14, v8, 7, 11
	v_and_or_b32 v12, v12, s14, v14
	v_mad_u64_u32 v[14:15], s[18:19], v12, s15, v[0:1]
	v_mov_b32_e32 v12, v15
	v_and_b32_e32 v2, 0x1fc, v6
	v_mad_u64_u32 v[12:13], s[18:19], v13, s15, v[12:13]
	v_lshlrev_b32_e32 v2, 1, v2
	v_mov_b32_e32 v15, v12
	v_lshl_add_u64 v[12:13], v[14:15], 0, v[2:3]
	v_add_co_u32_e32 v12, vcc, s16, v12
	v_lshl_add_u64 v[8:9], v[8:9], 0, s[50:51]
	s_nop 0
	v_addc_co_u32_e32 v13, vcc, 0, v13, vcc
	flat_load_dwordx2 v[222:223], v[12:13] offset:3584
	v_lshl_add_u64 v[6:7], v[6:7], 0, s[6:7]
	v_lshrrev_b64 v[12:13], 5, v[8:9]
	v_bfe_u32 v14, v8, 7, 11
	v_and_or_b32 v12, v12, s14, v14
	v_mad_u64_u32 v[14:15], s[18:19], v12, s15, v[0:1]
	v_mov_b32_e32 v12, v15
	v_and_b32_e32 v2, 0x1fc, v6
	v_mad_u64_u32 v[12:13], s[18:19], v13, s15, v[12:13]
	v_lshlrev_b32_e32 v2, 1, v2
	v_mov_b32_e32 v15, v12
	v_lshl_add_u64 v[12:13], v[14:15], 0, v[2:3]
	v_add_co_u32_e32 v12, vcc, s16, v12
	v_lshl_add_u64 v[8:9], v[8:9], 0, s[50:51]
	s_nop 0
	v_addc_co_u32_e32 v13, vcc, 0, v13, vcc
	flat_load_dwordx2 v[224:225], v[12:13] offset:3584
	v_lshl_add_u64 v[6:7], v[6:7], 0, s[6:7]
	v_lshrrev_b64 v[12:13], 5, v[8:9]
	v_bfe_u32 v14, v8, 7, 11
	v_and_or_b32 v12, v12, s14, v14
	v_mad_u64_u32 v[14:15], s[18:19], v12, s15, v[0:1]
	v_mov_b32_e32 v12, v15
	v_and_b32_e32 v2, 0x1fc, v6
	v_mad_u64_u32 v[12:13], s[18:19], v13, s15, v[12:13]
	v_lshlrev_b32_e32 v2, 1, v2
	v_mov_b32_e32 v15, v12
	v_lshl_add_u64 v[12:13], v[14:15], 0, v[2:3]
	v_add_co_u32_e32 v12, vcc, s16, v12
	v_lshl_add_u64 v[8:9], v[8:9], 0, s[50:51]
	s_nop 0
	v_addc_co_u32_e32 v13, vcc, 0, v13, vcc
	flat_load_dwordx2 v[226:227], v[12:13] offset:3584
	v_lshl_add_u64 v[6:7], v[6:7], 0, s[6:7]
	s_waitcnt vmcnt(0) lgkmcnt(0)
	v_lshlrev_b32_e32 v228, 16, v220
	v_and_b32_e32 v229, 0xffff0000, v220
	v_lshlrev_b32_e32 v230, 16, v221
	v_and_b32_e32 v231, 0xffff0000, v221
	flat_store_dwordx4 v[4:5], v[228:231]
	v_lshl_add_u64 v[4:5], v[4:5], 0, s[2:3]
	v_lshlrev_b32_e32 v232, 16, v222
	v_and_b32_e32 v233, 0xffff0000, v222
	v_lshlrev_b32_e32 v234, 16, v223
	v_and_b32_e32 v235, 0xffff0000, v223
	flat_store_dwordx4 v[4:5], v[232:235]
	v_lshl_add_u64 v[4:5], v[4:5], 0, s[2:3]
	v_lshlrev_b32_e32 v236, 16, v224
	v_and_b32_e32 v237, 0xffff0000, v224
	v_lshlrev_b32_e32 v238, 16, v225
	v_and_b32_e32 v239, 0xffff0000, v225
	flat_store_dwordx4 v[4:5], v[236:239]
	v_lshl_add_u64 v[4:5], v[4:5], 0, s[2:3]
	v_lshlrev_b32_e32 v240, 16, v226
	v_and_b32_e32 v241, 0xffff0000, v226
	v_lshlrev_b32_e32 v242, 16, v227
	v_and_b32_e32 v243, 0xffff0000, v227
	flat_store_dwordx4 v[4:5], v[240:243]
	v_lshl_add_u64 v[4:5], v[4:5], 0, s[2:3]
	s_add_u32 s92, s92, s93
	s_cmp_le_u32 s92, 0x100000
	s_cbranch_scc1 .Lpw3_batch
.Lpw3_rest:
	v_cmp_ge_u64_e32 vcc, s[12:13], v[8:9]
	s_and_b64 exec, exec, vcc
	s_cbranch_execz .LBB0_474
